# grid barrier: leaders no longer issue/wait for the per-XCD and top-level generation atomics (no reader left after the arrival-counter polling change)
# speedup vs baseline: 1.0171x; 1.0059x over previous
; __device__ __forceinline__ unsigned xb_ld(unsigned* p)              { return __hip_atomic_load(p, __ATOMIC_RELAXED, __HIP_MEMORY_SCOPE_AGENT); }
; __device__ __forceinline__ unsigned xb_add(unsigned* p, unsigned v) { return __hip_atomic_fetch_add(p, v, __ATOMIC_RELAXED, __HIP_MEMORY_SCOPE_AGENT); }
; #define XB_SPIN(cond, bar) do { unsigned _sp = 0; while (cond) { __builtin_amdgcn_s_sleep(1); \
;     if ((++_sp & 255u) == 0u) { if (xb_ld(&(bar)[XB_TMO])) break; if (_sp > XB_SPIN_CAP) { atomicAdd(&(bar)[XB_TMO], 1u); break; } } } } while (0)
; __device__ __forceinline__ void xcd_barrier(const XcdBarrier& b) {
;     ...
;             const unsigned og = xb_add(&bar[XB_TOP], 1u);
;             const unsigned tg = og / nx;
;             if (og + 1u == (tg + 1u) * nx) xb_add(&bar[XB_TOPGEN], 1u);
;             else XB_SPIN(xb_ld(&bar[XB_TOPGEN]) == tg, bar);
;             __builtin_amdgcn_fence(__ATOMIC_ACQUIRE, "agent");
;             xb_add(&bar[XB_XGEN(b.x)], 1u);
;             asm volatile("s_waitcnt vmcnt(0)" ::: "memory");
.LBB0_106:
	s_or_b64 exec, exec, s[6:7]
	s_and_saveexec_b64 s[6:7], s[10:11]
	s_cbranch_execz .LBB0_108
.LBB0_108:
	s_or_b64 exec, exec, s[6:7]
	s_mov_b64 s[6:7], exec
	v_mbcnt_lo_u32_b32 v0, s6, 0
	v_mbcnt_hi_u32_b32 v0, s7, v0
	v_cmp_eq_u32_e32 vcc, 0, v0
	s_waitcnt vmcnt(0)
	buffer_inv sc1
	s_and_saveexec_b64 s[8:9], vcc
	s_cbranch_execz .LBB0_110
	s_bcnt1_i32_b64 s6, s[6:7]
.LBB0_110:
	s_or_b64 exec, exec, s[8:9]
	s_waitcnt vmcnt(0)

; __device__ __forceinline__ unsigned xb_ld(unsigned* p)              { return __hip_atomic_load(p, __ATOMIC_RELAXED, __HIP_MEMORY_SCOPE_AGENT); }
; __device__ __forceinline__ unsigned xb_add(unsigned* p, unsigned v) { return __hip_atomic_fetch_add(p, v, __ATOMIC_RELAXED, __HIP_MEMORY_SCOPE_AGENT); }
; #define XB_SPIN(cond, bar) do { unsigned _sp = 0; while (cond) { __builtin_amdgcn_s_sleep(1); \
;     if ((++_sp & 255u) == 0u) { if (xb_ld(&(bar)[XB_TMO])) break; if (_sp > XB_SPIN_CAP) { atomicAdd(&(bar)[XB_TMO], 1u); break; } } } } while (0)
; __device__ __forceinline__ void xcd_barrier(const XcdBarrier& b) {
;     ...
;             const unsigned og = xb_add(&bar[XB_TOP], 1u);
;             const unsigned tg = og / nx;
;             if (og + 1u == (tg + 1u) * nx) xb_add(&bar[XB_TOPGEN], 1u);
;             else XB_SPIN(xb_ld(&bar[XB_TOPGEN]) == tg, bar);
;             __builtin_amdgcn_fence(__ATOMIC_ACQUIRE, "agent");
;             xb_add(&bar[XB_XGEN(b.x)], 1u);
;             asm volatile("s_waitcnt vmcnt(0)" ::: "memory");
.LBB0_389:
	s_or_b64 exec, exec, s[8:9]
	s_and_saveexec_b64 s[8:9], s[12:13]
	s_cbranch_execz .LBB0_391
.LBB0_391:
	s_or_b64 exec, exec, s[8:9]
	s_mov_b64 s[8:9], exec
	v_mbcnt_lo_u32_b32 v0, s8, 0
	v_mbcnt_hi_u32_b32 v0, s9, v0
	v_cmp_eq_u32_e32 vcc, 0, v0
	s_waitcnt vmcnt(0)
	buffer_inv sc1
	s_and_saveexec_b64 s[10:11], vcc
	s_cbranch_execz .LBB0_393
	s_bcnt1_i32_b64 s8, s[8:9]
.LBB0_393:
	s_or_b64 exec, exec, s[10:11]
	s_waitcnt vmcnt(0)

; __device__ __forceinline__ unsigned xb_ld(unsigned* p)              { return __hip_atomic_load(p, __ATOMIC_RELAXED, __HIP_MEMORY_SCOPE_AGENT); }
; __device__ __forceinline__ unsigned xb_add(unsigned* p, unsigned v) { return __hip_atomic_fetch_add(p, v, __ATOMIC_RELAXED, __HIP_MEMORY_SCOPE_AGENT); }
; #define XB_SPIN(cond, bar) do { unsigned _sp = 0; while (cond) { __builtin_amdgcn_s_sleep(1); \
;     if ((++_sp & 255u) == 0u) { if (xb_ld(&(bar)[XB_TMO])) break; if (_sp > XB_SPIN_CAP) { atomicAdd(&(bar)[XB_TMO], 1u); break; } } } } while (0)
; __device__ __forceinline__ void xcd_barrier(const XcdBarrier& b) {
;     ...
;             const unsigned og = xb_add(&bar[XB_TOP], 1u);
;             const unsigned tg = og / nx;
;             if (og + 1u == (tg + 1u) * nx) xb_add(&bar[XB_TOPGEN], 1u);
;             else XB_SPIN(xb_ld(&bar[XB_TOPGEN]) == tg, bar);
;             __builtin_amdgcn_fence(__ATOMIC_ACQUIRE, "agent");
;             xb_add(&bar[XB_XGEN(b.x)], 1u);
;             asm volatile("s_waitcnt vmcnt(0)" ::: "memory");
.LBB0_513:
	s_or_b64 exec, exec, s[6:7]
	s_and_saveexec_b64 s[6:7], s[10:11]
	s_cbranch_execz .LBB0_515
.LBB0_515:
	s_or_b64 exec, exec, s[6:7]
	s_mov_b64 s[6:7], exec
	v_mbcnt_lo_u32_b32 v0, s6, 0
	v_mbcnt_hi_u32_b32 v0, s7, v0
	v_cmp_eq_u32_e32 vcc, 0, v0
	s_waitcnt vmcnt(0)
	buffer_inv sc1
	s_and_saveexec_b64 s[8:9], vcc
	s_cbranch_execz .LBB0_517
	s_bcnt1_i32_b64 s6, s[6:7]
.LBB0_517:
	s_or_b64 exec, exec, s[8:9]
	s_waitcnt vmcnt(0)

; __device__ __forceinline__ unsigned xb_ld(unsigned* p)              { return __hip_atomic_load(p, __ATOMIC_RELAXED, __HIP_MEMORY_SCOPE_AGENT); }
; __device__ __forceinline__ unsigned xb_add(unsigned* p, unsigned v) { return __hip_atomic_fetch_add(p, v, __ATOMIC_RELAXED, __HIP_MEMORY_SCOPE_AGENT); }
; #define XB_SPIN(cond, bar) do { unsigned _sp = 0; while (cond) { __builtin_amdgcn_s_sleep(1); \
;     if ((++_sp & 255u) == 0u) { if (xb_ld(&(bar)[XB_TMO])) break; if (_sp > XB_SPIN_CAP) { atomicAdd(&(bar)[XB_TMO], 1u); break; } } } } while (0)
; __device__ __forceinline__ void xcd_barrier(const XcdBarrier& b) {
;     ...
;             const unsigned og = xb_add(&bar[XB_TOP], 1u);
;             const unsigned tg = og / nx;
;             if (og + 1u == (tg + 1u) * nx) xb_add(&bar[XB_TOPGEN], 1u);
;             else XB_SPIN(xb_ld(&bar[XB_TOPGEN]) == tg, bar);
;             __builtin_amdgcn_fence(__ATOMIC_ACQUIRE, "agent");
;             xb_add(&bar[XB_XGEN(b.x)], 1u);
;             asm volatile("s_waitcnt vmcnt(0)" ::: "memory");
.LBB0_607:
	s_or_b64 exec, exec, s[10:11]
	s_and_saveexec_b64 s[10:11], s[12:13]
	s_cbranch_execz .LBB0_609
.LBB0_609:
	s_or_b64 exec, exec, s[10:11]
	s_mov_b64 s[10:11], exec
	v_mbcnt_lo_u32_b32 v0, s10, 0
	v_mbcnt_hi_u32_b32 v0, s11, v0
	v_cmp_eq_u32_e32 vcc, 0, v0
	s_waitcnt vmcnt(0)
	buffer_inv sc1
	s_and_saveexec_b64 s[12:13], vcc
	s_cbranch_execz .LBB0_611
	s_bcnt1_i32_b64 s10, s[10:11]
.LBB0_611:
	s_or_b64 exec, exec, s[12:13]
	s_waitcnt vmcnt(0)

; __device__ __forceinline__ unsigned xb_ld(unsigned* p)              { return __hip_atomic_load(p, __ATOMIC_RELAXED, __HIP_MEMORY_SCOPE_AGENT); }
; __device__ __forceinline__ unsigned xb_add(unsigned* p, unsigned v) { return __hip_atomic_fetch_add(p, v, __ATOMIC_RELAXED, __HIP_MEMORY_SCOPE_AGENT); }
; #define XB_SPIN(cond, bar) do { unsigned _sp = 0; while (cond) { __builtin_amdgcn_s_sleep(1); \
;     if ((++_sp & 255u) == 0u) { if (xb_ld(&(bar)[XB_TMO])) break; if (_sp > XB_SPIN_CAP) { atomicAdd(&(bar)[XB_TMO], 1u); break; } } } } while (0)
; __device__ __forceinline__ void xcd_barrier(const XcdBarrier& b) {
;     ...
;             const unsigned og = xb_add(&bar[XB_TOP], 1u);
;             const unsigned tg = og / nx;
;             if (og + 1u == (tg + 1u) * nx) xb_add(&bar[XB_TOPGEN], 1u);
;             else XB_SPIN(xb_ld(&bar[XB_TOPGEN]) == tg, bar);
;             __builtin_amdgcn_fence(__ATOMIC_ACQUIRE, "agent");
;             xb_add(&bar[XB_XGEN(b.x)], 1u);
;             asm volatile("s_waitcnt vmcnt(0)" ::: "memory");
.LBB0_730:
	s_or_b64 exec, exec, s[8:9]
	s_and_saveexec_b64 s[8:9], s[12:13]
	s_cbranch_execz .LBB0_732
.LBB0_732:
	s_or_b64 exec, exec, s[8:9]
	s_mov_b64 s[8:9], exec
	v_mbcnt_lo_u32_b32 v0, s8, 0
	v_mbcnt_hi_u32_b32 v0, s9, v0
	v_cmp_eq_u32_e32 vcc, 0, v0
	s_waitcnt vmcnt(0)
	buffer_inv sc1
	s_and_saveexec_b64 s[10:11], vcc
	s_cbranch_execz .LBB0_734
	s_bcnt1_i32_b64 s8, s[8:9]
.LBB0_734:
	s_or_b64 exec, exec, s[10:11]
	s_waitcnt vmcnt(0)

; __device__ __forceinline__ unsigned xb_ld(unsigned* p)              { return __hip_atomic_load(p, __ATOMIC_RELAXED, __HIP_MEMORY_SCOPE_AGENT); }
; __device__ __forceinline__ unsigned xb_add(unsigned* p, unsigned v) { return __hip_atomic_fetch_add(p, v, __ATOMIC_RELAXED, __HIP_MEMORY_SCOPE_AGENT); }
; #define XB_SPIN(cond, bar) do { unsigned _sp = 0; while (cond) { __builtin_amdgcn_s_sleep(1); \
;     if ((++_sp & 255u) == 0u) { if (xb_ld(&(bar)[XB_TMO])) break; if (_sp > XB_SPIN_CAP) { atomicAdd(&(bar)[XB_TMO], 1u); break; } } } } while (0)
; __device__ __forceinline__ void xcd_barrier(const XcdBarrier& b) {
;     ...
;             const unsigned og = xb_add(&bar[XB_TOP], 1u);
;             const unsigned tg = og / nx;
;             if (og + 1u == (tg + 1u) * nx) xb_add(&bar[XB_TOPGEN], 1u);
;             else XB_SPIN(xb_ld(&bar[XB_TOPGEN]) == tg, bar);
;             __builtin_amdgcn_fence(__ATOMIC_ACQUIRE, "agent");
;             xb_add(&bar[XB_XGEN(b.x)], 1u);
;             asm volatile("s_waitcnt vmcnt(0)" ::: "memory");
.LBB0_808:
	s_or_b64 exec, exec, s[34:35]
	s_and_saveexec_b64 s[14:15], s[12:13]
	s_cbranch_execz .LBB0_810
.LBB0_810:
	s_or_b64 exec, exec, s[14:15]
	s_mov_b64 s[12:13], exec
	v_mbcnt_lo_u32_b32 v0, s12, 0
	v_mbcnt_hi_u32_b32 v0, s13, v0
	v_cmp_eq_u32_e32 vcc, 0, v0
	s_waitcnt vmcnt(0)
	buffer_inv sc1
	s_and_saveexec_b64 s[14:15], vcc
	s_cbranch_execz .LBB0_812
	s_bcnt1_i32_b64 s12, s[12:13]
.LBB0_812:
	s_or_b64 exec, exec, s[14:15]
	s_waitcnt vmcnt(0)

; __device__ __forceinline__ unsigned xb_ld(unsigned* p)              { return __hip_atomic_load(p, __ATOMIC_RELAXED, __HIP_MEMORY_SCOPE_AGENT); }
; __device__ __forceinline__ unsigned xb_add(unsigned* p, unsigned v) { return __hip_atomic_fetch_add(p, v, __ATOMIC_RELAXED, __HIP_MEMORY_SCOPE_AGENT); }
; #define XB_SPIN(cond, bar) do { unsigned _sp = 0; while (cond) { __builtin_amdgcn_s_sleep(1); \
;     if ((++_sp & 255u) == 0u) { if (xb_ld(&(bar)[XB_TMO])) break; if (_sp > XB_SPIN_CAP) { atomicAdd(&(bar)[XB_TMO], 1u); break; } } } } while (0)
; __device__ __forceinline__ void xcd_barrier(const XcdBarrier& b) {
;     ...
;             const unsigned og = xb_add(&bar[XB_TOP], 1u);
;             const unsigned tg = og / nx;
;             if (og + 1u == (tg + 1u) * nx) xb_add(&bar[XB_TOPGEN], 1u);
;             else XB_SPIN(xb_ld(&bar[XB_TOPGEN]) == tg, bar);
;             __builtin_amdgcn_fence(__ATOMIC_ACQUIRE, "agent");
;             xb_add(&bar[XB_XGEN(b.x)], 1u);
;             asm volatile("s_waitcnt vmcnt(0)" ::: "memory");
.LBB0_909:
	s_or_b64 exec, exec, s[8:9]
	s_and_saveexec_b64 s[8:9], s[12:13]
	s_cbranch_execz .LBB0_911
.LBB0_911:
	s_or_b64 exec, exec, s[8:9]
	s_mov_b64 s[8:9], exec
	v_mbcnt_lo_u32_b32 v0, s8, 0
	v_mbcnt_hi_u32_b32 v0, s9, v0
	v_cmp_eq_u32_e32 vcc, 0, v0
	s_waitcnt vmcnt(0)
	buffer_inv sc1
	s_and_saveexec_b64 s[10:11], vcc
	s_cbranch_execz .LBB0_913
	s_bcnt1_i32_b64 s8, s[8:9]
.LBB0_913:
	s_or_b64 exec, exec, s[10:11]
	s_waitcnt vmcnt(0)

; __device__ __forceinline__ unsigned xb_ld(unsigned* p)              { return __hip_atomic_load(p, __ATOMIC_RELAXED, __HIP_MEMORY_SCOPE_AGENT); }
; __device__ __forceinline__ unsigned xb_add(unsigned* p, unsigned v) { return __hip_atomic_fetch_add(p, v, __ATOMIC_RELAXED, __HIP_MEMORY_SCOPE_AGENT); }
; #define XB_SPIN(cond, bar) do { unsigned _sp = 0; while (cond) { __builtin_amdgcn_s_sleep(1); \
;     if ((++_sp & 255u) == 0u) { if (xb_ld(&(bar)[XB_TMO])) break; if (_sp > XB_SPIN_CAP) { atomicAdd(&(bar)[XB_TMO], 1u); break; } } } } while (0)
; __device__ __forceinline__ void xcd_barrier(const XcdBarrier& b) {
;     ...
;             const unsigned og = xb_add(&bar[XB_TOP], 1u);
;             const unsigned tg = og / nx;
;             if (og + 1u == (tg + 1u) * nx) xb_add(&bar[XB_TOPGEN], 1u);
;             else XB_SPIN(xb_ld(&bar[XB_TOPGEN]) == tg, bar);
;             __builtin_amdgcn_fence(__ATOMIC_ACQUIRE, "agent");
;             xb_add(&bar[XB_XGEN(b.x)], 1u);
;             asm volatile("s_waitcnt vmcnt(0)" ::: "memory");
.LBB0_996:
	s_or_b64 exec, exec, s[8:9]
	s_and_saveexec_b64 s[8:9], s[12:13]
	s_cbranch_execz .LBB0_998
.LBB0_998:
	s_or_b64 exec, exec, s[8:9]
	s_mov_b64 s[8:9], exec
	v_mbcnt_lo_u32_b32 v0, s8, 0
	v_mbcnt_hi_u32_b32 v0, s9, v0
	v_cmp_eq_u32_e32 vcc, 0, v0
	s_waitcnt vmcnt(0)
	buffer_inv sc1
	s_and_saveexec_b64 s[12:13], vcc
	s_cbranch_execz .LBB0_1000
	s_bcnt1_i32_b64 s8, s[8:9]
.LBB0_1000:
	s_or_b64 exec, exec, s[12:13]
	s_waitcnt vmcnt(0)

; __device__ __forceinline__ unsigned xb_ld(unsigned* p)              { return __hip_atomic_load(p, __ATOMIC_RELAXED, __HIP_MEMORY_SCOPE_AGENT); }
; __device__ __forceinline__ unsigned xb_add(unsigned* p, unsigned v) { return __hip_atomic_fetch_add(p, v, __ATOMIC_RELAXED, __HIP_MEMORY_SCOPE_AGENT); }
; #define XB_SPIN(cond, bar) do { unsigned _sp = 0; while (cond) { __builtin_amdgcn_s_sleep(1); \
;     if ((++_sp & 255u) == 0u) { if (xb_ld(&(bar)[XB_TMO])) break; if (_sp > XB_SPIN_CAP) { atomicAdd(&(bar)[XB_TMO], 1u); break; } } } } while (0)
; __device__ __forceinline__ void xcd_barrier(const XcdBarrier& b) {
;     ...
;             const unsigned og = xb_add(&bar[XB_TOP], 1u);
;             const unsigned tg = og / nx;
;             if (og + 1u == (tg + 1u) * nx) xb_add(&bar[XB_TOPGEN], 1u);
;             else XB_SPIN(xb_ld(&bar[XB_TOPGEN]) == tg, bar);
;             __builtin_amdgcn_fence(__ATOMIC_ACQUIRE, "agent");
;             xb_add(&bar[XB_XGEN(b.x)], 1u);
;             asm volatile("s_waitcnt vmcnt(0)" ::: "memory");
.LBB0_1064:
	s_or_b64 exec, exec, s[6:7]
	s_and_saveexec_b64 s[6:7], s[12:13]
	s_cbranch_execz .LBB0_1066
.LBB0_1066:
	s_or_b64 exec, exec, s[6:7]
	s_mov_b64 s[6:7], exec
	v_mbcnt_lo_u32_b32 v0, s6, 0
	v_mbcnt_hi_u32_b32 v0, s7, v0
	v_cmp_eq_u32_e32 vcc, 0, v0
	s_waitcnt vmcnt(0)
	buffer_inv sc1
	s_and_saveexec_b64 s[8:9], vcc
	s_cbranch_execz .LBB0_1068
	s_bcnt1_i32_b64 s3, s[6:7]
.LBB0_1068:
	s_or_b64 exec, exec, s[8:9]
	s_waitcnt vmcnt(0)
